# m30 + index selection: each histogram row is cleared right after its own level-2 scan (8 writes per row inside the row loop) instead of 16 writes after both rows, so the first row's clear overlaps the
# baseline (speedup 1.0000x reference)
.LBB0_1717:
	s_or_b64 exec, exec, s[42:43]
	s_waitcnt lgkmcnt(0)
	v_lshrrev_b32_e32 v6, 3, v2
	v_and_b32_e32 v13, 28, v6
	v_sub_u32_e32 v6, 0x7e4, v5
	v_and_b32_e32 v7, 0x7e4, v6
	v_lshrrev_b32_e32 v6, 3, v6
	v_bitop3_b32 v6, v6, v7, 28 bitop3:0x6c
	v_sub_u32_e32 v7, 0x7e8, v5
	v_and_b32_e32 v8, 0x7e8, v7
	v_lshrrev_b32_e32 v7, 3, v7
	v_bitop3_b32 v7, v7, v8, 28 bitop3:0x6c
	v_sub_u32_e32 v8, 0x7ec, v5
	v_and_b32_e32 v9, 0x7ec, v8
	v_lshrrev_b32_e32 v8, 3, v8
	v_bitop3_b32 v8, v8, v9, 28 bitop3:0x6c
	v_sub_u32_e32 v9, 0x7f0, v5
	v_and_b32_e32 v10, 0x7f0, v9
	v_lshrrev_b32_e32 v9, 3, v9
	v_bitop3_b32 v9, v9, v10, 28 bitop3:0x6c
	v_sub_u32_e32 v10, 0x7f4, v5
	v_and_b32_e32 v11, 0x7f4, v10
	v_lshrrev_b32_e32 v10, 3, v10
	v_bitop3_b32 v10, v10, v11, 28 bitop3:0x6c
	v_sub_u32_e32 v11, 0x7f8, v5
	v_and_b32_e32 v12, 0x7f8, v11
	v_lshrrev_b32_e32 v11, 3, v11
	v_bitop3_b32 v11, v11, v12, 28 bitop3:0x6c
	v_sub_u32_e32 v12, 0x7fc, v5
	v_and_b32_e32 v14, 0x7e0, v2
	v_and_b32_e32 v15, 0x7fc, v12
	v_lshrrev_b32_e32 v12, 3, v12
	v_bitop3_b32 v12, v12, v15, 28 bitop3:0x6c
	s_mov_b32 s8, 0
	s_mov_b64 s[0:1], -1
	v_lshlrev_b32_e32 v13, 2, v13
	v_lshlrev_b32_e32 v14, 2, v14
	v_mov_b64_e32 v[204:205], 0
	v_mov_b64_e32 v[206:207], 0
	s_barrier
	s_branch .LBB0_1720

.LBB0_1719:
	s_cmp_eq_u64 s[0:1], 0
	s_cselect_b32 s9, 0x2000, 0
	v_add_u32_e32 v203, s9, v3
	ds_write_b128 v203, v[204:207]
	ds_write_b128 v203, v[204:207] offset:1024
	ds_write_b128 v203, v[204:207] offset:2048
	ds_write_b128 v203, v[204:207] offset:3072
	ds_write_b128 v203, v[204:207] offset:4096
	ds_write_b128 v203, v[204:207] offset:5120
	ds_write_b128 v203, v[204:207] offset:6144
	ds_write_b128 v203, v[204:207] offset:7168
	s_xor_b64 s[10:11], s[0:1], -1
	s_mov_b32 s8, 1
	s_mov_b64 s[0:1], 0
	s_and_b64 vcc, exec, s[10:11]
	s_cbranch_vccnz .LBB0_1724

.LBB0_1724:
	s_mov_b32 s68, s69
	s_mov_b32 s70, s69
	s_mov_b32 s71, s69
	v_mov_b64_e32 v[6:7], s[68:69]
	v_mov_b64_e32 v[8:9], s[70:71]
	v_mov_b32_e32 v5, s84
	s_waitcnt lgkmcnt(0)
	s_barrier
	ds_read_b32 v5, v5
	s_waitcnt lgkmcnt(0)
	v_readfirstlane_b32 s0, v5
	s_cmp_lg_u32 s0, 0
	s_cbranch_scc0 .LBB0_1887
	v_readlane_b32 s0, v251, 31
	s_nop 1
	v_lshl_add_u32 v5, v167, 4, s0
	ds_read_b32 v6, v5 offset:8
	s_waitcnt lgkmcnt(0)
	v_cmp_ne_u32_e32 vcc, 0, v6
	s_and_saveexec_b64 s[42:43], vcc
	v_readlane_b32 s7, v251, 32
	s_cbranch_execz .LBB0_2046
	ds_read_b32 v6, v5
	s_and_b64 vcc, exec, s[28:29]
	s_cbranch_vccnz .LBB0_1736
	v_lshrrev_b32_e32 v7, 10, v171
	s_waitcnt lgkmcnt(0)
	v_cmp_eq_u32_e32 vcc, v7, v6
	s_and_saveexec_b64 s[0:1], vcc
	s_cbranch_execz .LBB0_1729
	v_and_b32_e32 v7, 0x3ff, v171
	v_add_u32_e32 v7, v7, v172
	v_lshrrev_b32_e32 v8, 3, v7
	v_bitop3_b32 v7, v8, v7, 28 bitop3:0x6c
	v_lshl_add_u32 v7, v7, 2, v40
	ds_add_u32 v7, v186
